# removed hipcc's vmcnt(0) flush in the GEMM unit preheaders (it drained epilogue stores and prefetched tiles before every unit) and relaxed the first two counted waits after an epilogue; on top of prev
# speedup vs baseline: 1.0040x; 1.0007x over previous
.LBB0_189:
	v_mov_b32_e32 v135, v1
	v_lshl_add_u64 v[8:9], s[36:37], 0, v[134:135]
	v_mov_b32_e32 v133, v1
	v_and_b32_e32 v189, 15, v190
	v_and_b32_e32 v7, 48, v190
	v_lshlrev_b32_e32 v16, 2, v190
	v_lshl_add_u64 v[10:11], s[36:37], 0, v[132:133]
	s_and_b32 s83, s23, 3
	s_lshl_b32 s6, s26, 13
	v_lshl_or_b32 v7, v189, 6, v7
	v_and_b32_e32 v16, 32, v16
	s_add_i32 m0, s17, 0x18000
	v_lshl_add_u64 v[8:9], v[8:9], 0, s[54:55]
	v_lshl_add_u64 v[12:13], s[24:25], 0, v[134:135]
	s_lshl_b32 s33, s26, 6
	v_bitop3_b32 v17, v7, s6, v16 bitop3:0xde
	s_lshl_b32 s6, s83, 12
	s_waitcnt vmcnt(2)
	s_barrier
	global_load_lds_dwordx4 v[8:9], off
	v_lshl_add_u64 v[8:9], v[10:11], 0, s[54:55]
	s_add_i32 m0, s17, 0x1a000
	s_add_i32 s72, s17, 0x8000
	s_add_i32 s73, s17, 0xa000
	v_lshl_add_u64 v[14:15], s[24:25], 0, v[132:133]
	v_bitop3_b32 v143, v7, s6, v16 bitop3:0xde
	global_load_lds_dwordx4 v[8:9], off
	v_lshl_add_u64 v[8:9], v[12:13], 0, s[54:55]
	s_mov_b32 m0, s72
	s_add_u32 s6, s36, 0x80080
	global_load_lds_dwordx4 v[8:9], off
	v_lshl_add_u64 v[8:9], v[14:15], 0, s[54:55]
	s_mov_b32 m0, s73
	s_addc_u32 s7, s37, 0
	global_load_lds_dwordx4 v[8:9], off
	s_add_i32 m0, s17, 0x1c000
	v_lshl_add_u64 v[8:9], s[6:7], 0, v[134:135]
	global_load_lds_dwordx4 v[8:9], off
	v_lshl_add_u64 v[8:9], s[6:7], 0, v[132:133]
	s_add_i32 m0, s17, 0x1e000
	v_lshlrev_b32_e32 v7, 15, v0
	global_load_lds_dwordx4 v[8:9], off
	v_and_b32_e32 v7, 0xffff0000, v7
	v_lshl_add_u32 v2, v2, 12, v7
	v_and_b32_e32 v0, 1, v0
	v_lshl_or_b32 v0, v0, 6, v2
	v_lshl_add_u32 v136, v3, 1, v0
	v_lshlrev_b32_e32 v0, 15, v4
	v_and_b32_e32 v0, 0xffff0000, v0
	v_lshl_add_u32 v0, v5, 12, v0
	v_and_b32_e32 v2, 1, v4
	s_waitcnt vmcnt(6)
	v_lshl_or_b32 v0, v2, 6, v0
	v_mov_b32_e32 v2, v1
	v_mov_b32_e32 v3, v1
	v_lshl_add_u32 v138, v6, 1, v0
	v_mov_b32_e32 v0, v1
	v_mov_b32_e32 v68, 0
	v_add_u32_e32 v144, 0, v17
	v_mov_b64_e32 v[6:7], v[2:3]
	v_mov_b64_e32 v[10:11], v[2:3]
	v_mov_b64_e32 v[14:15], v[2:3]
	v_mov_b64_e32 v[18:19], v[2:3]
	v_mov_b64_e32 v[22:23], v[2:3]
	v_mov_b64_e32 v[26:27], v[2:3]
	v_mov_b64_e32 v[30:31], v[2:3]
	v_mov_b64_e32 v[34:35], v[2:3]
	v_mov_b64_e32 v[38:39], v[2:3]
	v_mov_b64_e32 v[42:43], v[2:3]
	v_mov_b64_e32 v[46:47], v[2:3]
	v_mov_b64_e32 v[50:51], v[2:3]
	v_mov_b64_e32 v[54:55], v[2:3]
	v_mov_b64_e32 v[58:59], v[2:3]
	v_mov_b64_e32 v[62:63], v[2:3]
	v_mov_b64_e32 v[66:67], v[2:3]
	s_sext_i32_i8 s22, s22
	v_or_b32_e32 v142, s33, v189
	v_mov_b32_e32 v137, v1
	v_mov_b32_e32 v139, v1
	s_mov_b32 s84, 0
	v_mov_b64_e32 v[4:5], v[0:1]
	v_mov_b64_e32 v[8:9], v[0:1]
	v_mov_b64_e32 v[12:13], v[0:1]
	v_mov_b64_e32 v[16:17], v[0:1]
	v_mov_b64_e32 v[20:21], v[0:1]
	v_mov_b64_e32 v[24:25], v[0:1]
	v_mov_b64_e32 v[28:29], v[0:1]
	v_mov_b64_e32 v[32:33], v[0:1]
	v_mov_b64_e32 v[36:37], v[0:1]
	v_mov_b64_e32 v[40:41], v[0:1]
	v_mov_b64_e32 v[44:45], v[0:1]
	v_mov_b64_e32 v[48:49], v[0:1]
	v_mov_b64_e32 v[52:53], v[0:1]
	v_mov_b64_e32 v[56:57], v[0:1]
	v_mov_b64_e32 v[60:61], v[0:1]
	v_mov_b64_e32 v[64:65], v[0:1]
	v_mov_b32_e32 v69, v68
	v_mov_b32_e32 v70, v68
	v_mov_b32_e32 v71, v68
	v_mov_b32_e32 v72, v68
	v_mov_b32_e32 v73, v68
	v_mov_b32_e32 v74, v68
	v_mov_b32_e32 v75, v68
	v_mov_b32_e32 v76, v68
	v_mov_b32_e32 v77, v68
	v_mov_b32_e32 v78, v68
	v_mov_b32_e32 v79, v68
	v_mov_b32_e32 v80, v68
	v_mov_b32_e32 v81, v68
	v_mov_b32_e32 v82, v68
	v_mov_b32_e32 v83, v68
	v_mov_b32_e32 v84, v68
	v_mov_b32_e32 v85, v68
	v_mov_b32_e32 v86, v68
	v_mov_b32_e32 v87, v68
	v_mov_b32_e32 v88, v68
	v_mov_b32_e32 v89, v68
	v_mov_b32_e32 v90, v68
	v_mov_b32_e32 v91, v68
	v_mov_b32_e32 v92, v68
	v_mov_b32_e32 v93, v68
	v_mov_b32_e32 v94, v68
	v_mov_b32_e32 v95, v68
	v_mov_b32_e32 v96, v68
	v_mov_b32_e32 v97, v68
	v_mov_b32_e32 v98, v68
	v_mov_b32_e32 v99, v68
	v_mov_b32_e32 v100, v68
	v_mov_b32_e32 v101, v68
	v_mov_b32_e32 v102, v68
	v_mov_b32_e32 v103, v68
	v_mov_b32_e32 v104, v68
	v_mov_b32_e32 v105, v68
	v_mov_b32_e32 v106, v68
	v_mov_b32_e32 v107, v68
	v_mov_b32_e32 v108, v68
	v_mov_b32_e32 v109, v68
	v_mov_b32_e32 v110, v68
	v_mov_b32_e32 v111, v68
	v_mov_b32_e32 v112, v68
	v_mov_b32_e32 v113, v68
	v_mov_b32_e32 v114, v68
	v_mov_b32_e32 v115, v68
	v_mov_b32_e32 v116, v68
	v_mov_b32_e32 v117, v68
	v_mov_b32_e32 v118, v68
	v_mov_b32_e32 v119, v68
	v_mov_b32_e32 v120, v68
	v_mov_b32_e32 v121, v68
	v_mov_b32_e32 v122, v68
	v_mov_b32_e32 v123, v68
	v_mov_b32_e32 v124, v68
	v_mov_b32_e32 v125, v68
	v_mov_b32_e32 v126, v68
	v_mov_b32_e32 v127, v68
	v_mov_b32_e32 v128, v68
	v_mov_b32_e32 v129, v68
	v_mov_b32_e32 v130, v68
	v_mov_b32_e32 v131, v68
	s_barrier

.LBB0_429:
	s_ashr_i32 s27, s26, 31
	s_lshl_b64 s[28:29], s[26:27], 18
	s_cmp_eq_u32 s44, 0
	s_cselect_b32 s9, s79, s83
	s_cselect_b32 s7, s80, s84
	s_cselect_b32 s21, s81, s77
	s_cselect_b32 s27, s82, s85
	s_add_u32 s28, s9, s28
	s_addc_u32 s29, s7, s29
	s_and_b64 s[30:31], s[22:23], exec
	s_cselect_b32 s7, s29, s37
	s_cselect_b32 s9, s28, s36
	s_ashr_i32 s25, s24, 31
	s_lshl_b64 s[30:31], s[24:25], 18
	s_add_u32 s30, s21, s30
	s_addc_u32 s31, s27, s31
	s_and_b64 s[38:39], s[22:23], exec
	s_cselect_b32 s21, s31, s35
	s_cselect_b32 s25, s30, s34
	s_add_u32 s27, s34, 0x100
	s_addc_u32 s45, s35, 0
	s_add_u32 s34, s36, 0x20080
	v_mov_b32_e32 v2, 0
	s_addc_u32 s35, s37, 0
	s_mov_b32 s48, -2
	v_mov_b32_e32 v3, v2
	v_mov_b32_e32 v4, v2
	v_mov_b32_e32 v5, v2
	v_mov_b32_e32 v6, v2
	v_mov_b32_e32 v7, v2
	v_mov_b32_e32 v8, v2
	v_mov_b32_e32 v9, v2
	v_mov_b32_e32 v18, v2
	v_mov_b32_e32 v19, v2
	v_mov_b32_e32 v20, v2
	v_mov_b32_e32 v21, v2
	v_mov_b32_e32 v22, v2
	v_mov_b32_e32 v23, v2
	v_mov_b32_e32 v24, v2
	v_mov_b32_e32 v25, v2
	v_mov_b32_e32 v34, v2
	v_mov_b32_e32 v35, v2
	v_mov_b32_e32 v36, v2
	v_mov_b32_e32 v37, v2
	v_mov_b32_e32 v38, v2
	v_mov_b32_e32 v39, v2
	v_mov_b32_e32 v40, v2
	v_mov_b32_e32 v41, v2
	v_mov_b32_e32 v50, v2
	v_mov_b32_e32 v51, v2
	v_mov_b32_e32 v52, v2
	v_mov_b32_e32 v53, v2
	v_mov_b32_e32 v54, v2
	v_mov_b32_e32 v55, v2
	v_mov_b32_e32 v56, v2
	v_mov_b32_e32 v57, v2
	v_mov_b32_e32 v10, v2
	v_mov_b32_e32 v11, v2
	v_mov_b32_e32 v12, v2
	v_mov_b32_e32 v13, v2
	v_mov_b32_e32 v14, v2
	v_mov_b32_e32 v15, v2
	v_mov_b32_e32 v16, v2
	v_mov_b32_e32 v17, v2
	v_mov_b32_e32 v26, v2
	v_mov_b32_e32 v27, v2
	v_mov_b32_e32 v28, v2
	v_mov_b32_e32 v29, v2
	v_mov_b32_e32 v30, v2
	v_mov_b32_e32 v31, v2
	v_mov_b32_e32 v32, v2
	v_mov_b32_e32 v33, v2
	v_mov_b32_e32 v42, v2
	v_mov_b32_e32 v43, v2
	v_mov_b32_e32 v44, v2
	v_mov_b32_e32 v45, v2
	v_mov_b32_e32 v46, v2
	v_mov_b32_e32 v47, v2
	v_mov_b32_e32 v48, v2
	v_mov_b32_e32 v49, v2
	v_mov_b32_e32 v58, v2
	v_mov_b32_e32 v59, v2
	v_mov_b32_e32 v60, v2
	v_mov_b32_e32 v61, v2
	v_mov_b32_e32 v62, v2
	v_mov_b32_e32 v63, v2
	v_mov_b32_e32 v64, v2
	v_mov_b32_e32 v65, v2
	v_mov_b32_e32 v66, v2
	v_mov_b32_e32 v67, v2
	v_mov_b32_e32 v68, v2
	v_mov_b32_e32 v69, v2
	v_mov_b32_e32 v70, v2
	v_mov_b32_e32 v71, v2
	v_mov_b32_e32 v72, v2
	v_mov_b32_e32 v73, v2
	v_mov_b32_e32 v82, v2
	v_mov_b32_e32 v83, v2
	v_mov_b32_e32 v84, v2
	v_mov_b32_e32 v85, v2
	v_mov_b32_e32 v86, v2
	v_mov_b32_e32 v87, v2
	v_mov_b32_e32 v88, v2
	v_mov_b32_e32 v89, v2
	v_mov_b32_e32 v98, v2
	v_mov_b32_e32 v99, v2
	v_mov_b32_e32 v100, v2
	v_mov_b32_e32 v101, v2
	v_mov_b32_e32 v102, v2
	v_mov_b32_e32 v103, v2
	v_mov_b32_e32 v104, v2
	v_mov_b32_e32 v105, v2
	v_mov_b32_e32 v114, v2
	v_mov_b32_e32 v115, v2
	v_mov_b32_e32 v116, v2
	v_mov_b32_e32 v117, v2
	v_mov_b32_e32 v118, v2
	v_mov_b32_e32 v119, v2
	v_mov_b32_e32 v120, v2
	v_mov_b32_e32 v121, v2
	v_mov_b32_e32 v74, v2
	v_mov_b32_e32 v75, v2
	v_mov_b32_e32 v76, v2
	v_mov_b32_e32 v77, v2
	v_mov_b32_e32 v78, v2
	v_mov_b32_e32 v79, v2
	v_mov_b32_e32 v80, v2
	v_mov_b32_e32 v81, v2
	v_mov_b32_e32 v90, v2
	v_mov_b32_e32 v91, v2
	v_mov_b32_e32 v92, v2
	v_mov_b32_e32 v93, v2
	v_mov_b32_e32 v94, v2
	v_mov_b32_e32 v95, v2
	v_mov_b32_e32 v96, v2
	v_mov_b32_e32 v97, v2
	v_mov_b32_e32 v106, v2
	v_mov_b32_e32 v107, v2
	v_mov_b32_e32 v108, v2
	v_mov_b32_e32 v109, v2
	v_mov_b32_e32 v110, v2
	v_mov_b32_e32 v111, v2
	v_mov_b32_e32 v112, v2
	v_mov_b32_e32 v113, v2
	v_mov_b32_e32 v122, v2
	v_mov_b32_e32 v123, v2
	v_mov_b32_e32 v124, v2
	v_mov_b32_e32 v125, v2
	v_mov_b32_e32 v126, v2
	v_mov_b32_e32 v127, v2
	v_mov_b32_e32 v128, v2
	v_mov_b32_e32 v129, v2
	s_cmp_eq_u32 s99, 0
	s_cbranch_scc1 .LBB0_430

.LBB0_604:
	s_ashr_i32 s35, s34, 31
	s_lshl_b64 s[36:37], s[34:35], 20
	s_add_u32 s36, s73, s36
	s_addc_u32 s37, s89, s37
	s_and_b64 s[38:39], s[6:7], exec
	s_cselect_b32 s11, s37, s81
	s_cselect_b32 s35, s36, s80
	s_ashr_i32 s31, s30, 31
	s_lshl_b64 s[38:39], s[30:31], 20
	s_add_u32 s38, s97, s38
	s_addc_u32 s39, s65, s39
	s_and_b64 s[82:83], s[6:7], exec
	s_cselect_b32 s31, s39, s9
	s_cselect_b32 s79, s38, s8
	s_add_u32 s84, s8, 0x100
	s_addc_u32 s85, s9, 0
	s_add_u32 s8, s80, 0x80080
	v_mov_b32_e32 v2, 0
	s_addc_u32 s9, s81, 0
	s_mov_b32 s86, -2
	v_mov_b32_e32 v3, v2
	v_mov_b32_e32 v4, v2
	v_mov_b32_e32 v5, v2
	v_mov_b32_e32 v6, v2
	v_mov_b32_e32 v7, v2
	v_mov_b32_e32 v8, v2
	v_mov_b32_e32 v9, v2
	v_mov_b32_e32 v18, v2
	v_mov_b32_e32 v19, v2
	v_mov_b32_e32 v20, v2
	v_mov_b32_e32 v21, v2
	v_mov_b32_e32 v22, v2
	v_mov_b32_e32 v23, v2
	v_mov_b32_e32 v24, v2
	v_mov_b32_e32 v25, v2
	v_mov_b32_e32 v34, v2
	v_mov_b32_e32 v35, v2
	v_mov_b32_e32 v36, v2
	v_mov_b32_e32 v37, v2
	v_mov_b32_e32 v38, v2
	v_mov_b32_e32 v39, v2
	v_mov_b32_e32 v40, v2
	v_mov_b32_e32 v41, v2
	v_mov_b32_e32 v50, v2
	v_mov_b32_e32 v51, v2
	v_mov_b32_e32 v52, v2
	v_mov_b32_e32 v53, v2
	v_mov_b32_e32 v54, v2
	v_mov_b32_e32 v55, v2
	v_mov_b32_e32 v56, v2
	v_mov_b32_e32 v57, v2
	v_mov_b32_e32 v10, v2
	v_mov_b32_e32 v11, v2
	v_mov_b32_e32 v12, v2
	v_mov_b32_e32 v13, v2
	v_mov_b32_e32 v14, v2
	v_mov_b32_e32 v15, v2
	v_mov_b32_e32 v16, v2
	v_mov_b32_e32 v17, v2
	v_mov_b32_e32 v26, v2
	v_mov_b32_e32 v27, v2
	v_mov_b32_e32 v28, v2
	v_mov_b32_e32 v29, v2
	v_mov_b32_e32 v30, v2
	v_mov_b32_e32 v31, v2
	v_mov_b32_e32 v32, v2
	v_mov_b32_e32 v33, v2
	v_mov_b32_e32 v42, v2
	v_mov_b32_e32 v43, v2
	v_mov_b32_e32 v44, v2
	v_mov_b32_e32 v45, v2
	v_mov_b32_e32 v46, v2
	v_mov_b32_e32 v47, v2
	v_mov_b32_e32 v48, v2
	v_mov_b32_e32 v49, v2
	v_mov_b32_e32 v58, v2
	v_mov_b32_e32 v59, v2
	v_mov_b32_e32 v60, v2
	v_mov_b32_e32 v61, v2
	v_mov_b32_e32 v62, v2
	v_mov_b32_e32 v63, v2
	v_mov_b32_e32 v64, v2
	v_mov_b32_e32 v65, v2
	v_mov_b32_e32 v66, v2
	v_mov_b32_e32 v67, v2
	v_mov_b32_e32 v68, v2
	v_mov_b32_e32 v69, v2
	v_mov_b32_e32 v70, v2
	v_mov_b32_e32 v71, v2
	v_mov_b32_e32 v72, v2
	v_mov_b32_e32 v73, v2
	v_mov_b32_e32 v82, v2
	v_mov_b32_e32 v83, v2
	v_mov_b32_e32 v84, v2
	v_mov_b32_e32 v85, v2
	v_mov_b32_e32 v86, v2
	v_mov_b32_e32 v87, v2
	v_mov_b32_e32 v88, v2
	v_mov_b32_e32 v89, v2
	v_mov_b32_e32 v98, v2
	v_mov_b32_e32 v99, v2
	v_mov_b32_e32 v100, v2
	v_mov_b32_e32 v101, v2
	v_mov_b32_e32 v102, v2
	v_mov_b32_e32 v103, v2
	v_mov_b32_e32 v104, v2
	v_mov_b32_e32 v105, v2
	v_mov_b32_e32 v114, v2
	v_mov_b32_e32 v115, v2
	v_mov_b32_e32 v116, v2
	v_mov_b32_e32 v117, v2
	v_mov_b32_e32 v118, v2
	v_mov_b32_e32 v119, v2
	v_mov_b32_e32 v120, v2
	v_mov_b32_e32 v121, v2
	v_mov_b32_e32 v74, v2
	v_mov_b32_e32 v75, v2
	v_mov_b32_e32 v76, v2
	v_mov_b32_e32 v77, v2
	v_mov_b32_e32 v78, v2
	v_mov_b32_e32 v79, v2
	v_mov_b32_e32 v80, v2
	v_mov_b32_e32 v81, v2
	v_mov_b32_e32 v90, v2
	v_mov_b32_e32 v91, v2
	v_mov_b32_e32 v92, v2
	v_mov_b32_e32 v93, v2
	v_mov_b32_e32 v94, v2
	v_mov_b32_e32 v95, v2
	v_mov_b32_e32 v96, v2
	v_mov_b32_e32 v97, v2
	v_mov_b32_e32 v106, v2
	v_mov_b32_e32 v107, v2
	v_mov_b32_e32 v108, v2
	v_mov_b32_e32 v109, v2
	v_mov_b32_e32 v110, v2
	v_mov_b32_e32 v111, v2
	v_mov_b32_e32 v112, v2
	v_mov_b32_e32 v113, v2
	v_mov_b32_e32 v122, v2
	v_mov_b32_e32 v123, v2
	v_mov_b32_e32 v124, v2
	v_mov_b32_e32 v125, v2
	v_mov_b32_e32 v130, v2
	v_mov_b32_e32 v131, v2
	v_mov_b32_e32 v132, v2
	v_mov_b32_e32 v133, v2
	s_cmp_eq_u32 s99, 0
	s_cbranch_scc1 .LBB0_605

.LBB0_877:
	v_lshl_add_u64 v[10:11], s[36:37], 0, v[0:1]
	v_mov_b32_e32 v131, v1
	v_and_b32_e32 v221, 15, v212
	v_and_b32_e32 v18, 48, v212
	v_lshlrev_b32_e32 v19, 2, v212
	v_lshl_add_u64 v[12:13], s[36:37], 0, v[130:131]
	s_and_b32 s33, s19, 3
	s_lshl_b32 s4, s7, 13
	v_lshl_or_b32 v18, v221, 6, v18
	v_and_b32_e32 v19, 32, v19
	s_add_i32 m0, s21, 0x18000
	v_lshl_add_u64 v[10:11], v[10:11], 0, s[54:55]
	v_lshl_add_u64 v[14:15], s[24:25], 0, v[0:1]
	s_lshl_b32 s80, s7, 6
	v_bitop3_b32 v20, v18, s4, v19 bitop3:0xde
	s_lshl_b32 s4, s33, 12
	s_waitcnt vmcnt(2)
	s_barrier
	global_load_lds_dwordx4 v[10:11], off
	v_lshl_add_u64 v[10:11], v[12:13], 0, s[54:55]
	s_add_i32 m0, s21, 0x1a000
	s_add_i32 s68, s21, 0x8000
	s_add_i32 s69, s21, 0xa000
	v_lshl_add_u64 v[16:17], s[24:25], 0, v[130:131]
	v_bitop3_b32 v140, v18, s4, v19 bitop3:0xde
	global_load_lds_dwordx4 v[10:11], off
	v_lshl_add_u64 v[10:11], v[14:15], 0, s[54:55]
	s_mov_b32 m0, s68
	s_add_u32 s4, s36, 0x80080
	global_load_lds_dwordx4 v[10:11], off
	v_lshl_add_u64 v[10:11], v[16:17], 0, s[54:55]
	s_mov_b32 m0, s69
	s_addc_u32 s5, s37, 0
	global_load_lds_dwordx4 v[10:11], off
	s_add_i32 m0, s21, 0x1c000
	v_lshl_add_u64 v[10:11], s[4:5], 0, v[0:1]
	global_load_lds_dwordx4 v[10:11], off
	v_lshl_add_u64 v[10:11], s[4:5], 0, v[130:131]
	s_add_i32 m0, s21, 0x1e000
	v_lshlrev_b32_e32 v2, 14, v2
	global_load_lds_dwordx4 v[10:11], off
	v_lshlrev_b32_e32 v6, 14, v6
	v_and_b32_e32 v2, 0x7fff8000, v2
	v_and_b32_e32 v6, 0x7fff8000, v6
	v_lshl_add_u32 v2, v3, 11, v2
	s_waitcnt vmcnt(6)
	v_lshl_add_u32 v6, v7, 11, v6
	v_or_b32_e32 v2, v2, v4
	v_or_b32_e32 v6, v6, v8
	v_add_lshl_u32 v134, v2, v5, 1
	v_mov_b32_e32 v2, 0
	s_sext_i32_i8 s18, s6
	v_or_b32_e32 v211, s80, v221
	v_add_lshl_u32 v132, v6, v9, 1
	v_mov_b32_e32 v133, v1
	v_mov_b32_e32 v135, v1
	s_mov_b32 s70, 0
	v_add_u32_e32 v141, 0, v20
	v_mov_b32_e32 v3, v2
	v_mov_b32_e32 v4, v2
	v_mov_b32_e32 v5, v2
	v_mov_b32_e32 v6, v2
	v_mov_b32_e32 v7, v2
	v_mov_b32_e32 v8, v2
	v_mov_b32_e32 v9, v2
	v_mov_b32_e32 v14, v2
	v_mov_b32_e32 v15, v2
	v_mov_b32_e32 v16, v2
	v_mov_b32_e32 v17, v2
	v_mov_b32_e32 v22, v2
	v_mov_b32_e32 v23, v2
	v_mov_b32_e32 v24, v2
	v_mov_b32_e32 v25, v2
	v_mov_b32_e32 v30, v2
	v_mov_b32_e32 v31, v2
	v_mov_b32_e32 v32, v2
	v_mov_b32_e32 v33, v2
	v_mov_b32_e32 v38, v2
	v_mov_b32_e32 v39, v2
	v_mov_b32_e32 v40, v2
	v_mov_b32_e32 v41, v2
	v_mov_b32_e32 v46, v2
	v_mov_b32_e32 v47, v2
	v_mov_b32_e32 v48, v2
	v_mov_b32_e32 v49, v2
	v_mov_b32_e32 v54, v2
	v_mov_b32_e32 v55, v2
	v_mov_b32_e32 v56, v2
	v_mov_b32_e32 v57, v2
	v_mov_b32_e32 v10, v2
	v_mov_b32_e32 v11, v2
	v_mov_b32_e32 v12, v2
	v_mov_b32_e32 v13, v2
	v_mov_b32_e32 v18, v2
	v_mov_b32_e32 v19, v2
	v_mov_b32_e32 v20, v2
	v_mov_b32_e32 v21, v2
	v_mov_b32_e32 v26, v2
	v_mov_b32_e32 v27, v2
	v_mov_b32_e32 v28, v2
	v_mov_b32_e32 v29, v2
	v_mov_b32_e32 v34, v2
	v_mov_b32_e32 v35, v2
	v_mov_b32_e32 v36, v2
	v_mov_b32_e32 v37, v2
	v_mov_b32_e32 v42, v2
	v_mov_b32_e32 v43, v2
	v_mov_b32_e32 v44, v2
	v_mov_b32_e32 v45, v2
	v_mov_b32_e32 v50, v2
	v_mov_b32_e32 v51, v2
	v_mov_b32_e32 v52, v2
	v_mov_b32_e32 v53, v2
	v_mov_b32_e32 v58, v2
	v_mov_b32_e32 v59, v2
	v_mov_b32_e32 v60, v2
	v_mov_b32_e32 v61, v2
	v_mov_b32_e32 v62, v2
	v_mov_b32_e32 v63, v2
	v_mov_b32_e32 v64, v2
	v_mov_b32_e32 v65, v2
	v_mov_b32_e32 v66, v2
	v_mov_b32_e32 v67, v2
	v_mov_b32_e32 v68, v2
	v_mov_b32_e32 v69, v2
	v_mov_b32_e32 v70, v2
	v_mov_b32_e32 v71, v2
	v_mov_b32_e32 v72, v2
	v_mov_b32_e32 v73, v2
	v_mov_b32_e32 v78, v2
	v_mov_b32_e32 v79, v2
	v_mov_b32_e32 v80, v2
	v_mov_b32_e32 v81, v2
	v_mov_b32_e32 v86, v2
	v_mov_b32_e32 v87, v2
	v_mov_b32_e32 v88, v2
	v_mov_b32_e32 v89, v2
	v_mov_b32_e32 v94, v2
	v_mov_b32_e32 v95, v2
	v_mov_b32_e32 v96, v2
	v_mov_b32_e32 v97, v2
	v_mov_b32_e32 v102, v2
	v_mov_b32_e32 v103, v2
	v_mov_b32_e32 v104, v2
	v_mov_b32_e32 v105, v2
	v_mov_b32_e32 v114, v2
	v_mov_b32_e32 v115, v2
	v_mov_b32_e32 v116, v2
	v_mov_b32_e32 v117, v2
	v_mov_b32_e32 v118, v2
	v_mov_b32_e32 v119, v2
	v_mov_b32_e32 v120, v2
	v_mov_b32_e32 v121, v2
	v_mov_b32_e32 v74, v2
	v_mov_b32_e32 v75, v2
	v_mov_b32_e32 v76, v2
	v_mov_b32_e32 v77, v2
	v_mov_b32_e32 v82, v2
	v_mov_b32_e32 v83, v2
	v_mov_b32_e32 v84, v2
	v_mov_b32_e32 v85, v2
	v_mov_b32_e32 v90, v2
	v_mov_b32_e32 v91, v2
	v_mov_b32_e32 v92, v2
	v_mov_b32_e32 v93, v2
	v_mov_b32_e32 v98, v2
	v_mov_b32_e32 v99, v2
	v_mov_b32_e32 v100, v2
	v_mov_b32_e32 v101, v2
	v_mov_b32_e32 v106, v2
	v_mov_b32_e32 v107, v2
	v_mov_b32_e32 v108, v2
	v_mov_b32_e32 v109, v2
	v_mov_b32_e32 v110, v2
	v_mov_b32_e32 v111, v2
	v_mov_b32_e32 v112, v2
	v_mov_b32_e32 v113, v2
	v_mov_b32_e32 v122, v2
	v_mov_b32_e32 v123, v2
	v_mov_b32_e32 v124, v2
	v_mov_b32_e32 v125, v2
	v_mov_b32_e32 v126, v2
	v_mov_b32_e32 v127, v2
	v_mov_b32_e32 v128, v2
	v_mov_b32_e32 v129, v2
	s_barrier

.LBB0_939:
	v_lshl_add_u64 v[8:9], s[38:39], 0, v[0:1]
	v_mov_b32_e32 v115, v1
	v_and_b32_e32 v221, 15, v220
	v_and_b32_e32 v16, 48, v220
	v_lshlrev_b32_e32 v17, 2, v220
	v_lshl_add_u64 v[10:11], s[38:39], 0, v[114:115]
	s_and_b32 s33, s17, 3
	s_lshl_b32 s4, s28, 13
	v_lshl_or_b32 v16, v221, 6, v16
	v_and_b32_e32 v17, 32, v17
	s_add_i32 m0, s19, 0x18000
	v_lshl_add_u64 v[8:9], v[8:9], 0, s[54:55]
	v_lshl_add_u64 v[12:13], s[26:27], 0, v[0:1]
	s_lshl_b32 s86, s28, 6
	v_bitop3_b32 v18, v16, s4, v17 bitop3:0xde
	s_lshl_b32 s4, s33, 12
	s_waitcnt vmcnt(2)
	s_barrier
	global_load_lds_dwordx4 v[8:9], off
	v_lshl_add_u64 v[8:9], v[10:11], 0, s[54:55]
	s_add_i32 m0, s19, 0x1a000
	s_add_i32 s68, s19, 0x8000
	s_add_i32 s69, s19, 0xa000
	v_lshl_add_u64 v[14:15], s[26:27], 0, v[114:115]
	v_bitop3_b32 v124, v16, s4, v17 bitop3:0xde
	global_load_lds_dwordx4 v[8:9], off
	v_lshl_add_u64 v[8:9], v[12:13], 0, s[54:55]
	s_mov_b32 m0, s68
	s_add_u32 s4, s38, 0x80080
	global_load_lds_dwordx4 v[8:9], off
	v_lshl_add_u64 v[8:9], v[14:15], 0, s[54:55]
	s_mov_b32 m0, s69
	s_addc_u32 s5, s39, 0
	global_load_lds_dwordx4 v[8:9], off
	s_add_i32 m0, s19, 0x1c000
	v_lshl_add_u64 v[8:9], s[4:5], 0, v[0:1]
	global_load_lds_dwordx4 v[8:9], off
	v_lshl_add_u64 v[8:9], s[4:5], 0, v[114:115]
	s_add_i32 m0, s19, 0x1e000
	s_sext_i32_i8 s16, s16
	global_load_lds_dwordx4 v[8:9], off
	v_lshlrev_b32_e32 v8, 15, v5
	v_and_b32_e32 v8, 0xffff0000, v8
	v_lshl_add_u32 v6, v6, 12, v8
	v_and_b32_e32 v5, 1, v5
	v_lshl_or_b32 v5, v5, 6, v6
	v_lshl_add_u32 v116, v7, 1, v5
	v_lshlrev_b32_e32 v5, 15, v2
	v_and_b32_e32 v5, 0xffff0000, v5
	v_lshl_add_u32 v3, v3, 12, v5
	v_and_b32_e32 v2, 1, v2
	s_waitcnt vmcnt(6)
	v_lshl_or_b32 v2, v2, 6, v3
	v_lshl_add_u32 v118, v4, 1, v2
	v_mov_b32_e32 v2, 0
	v_or_b32_e32 v151, s86, v221
	v_mov_b32_e32 v117, v1
	v_mov_b32_e32 v119, v1
	s_mov_b32 s70, 0
	v_add_u32_e32 v125, 0, v18
	v_mov_b32_e32 v3, v2
	v_mov_b32_e32 v4, v2
	v_mov_b32_e32 v5, v2
	v_mov_b32_e32 v6, v2
	v_mov_b32_e32 v7, v2
	v_mov_b32_e32 v8, v2
	v_mov_b32_e32 v9, v2
	v_mov_b32_e32 v18, v2
	v_mov_b32_e32 v19, v2
	v_mov_b32_e32 v20, v2
	v_mov_b32_e32 v21, v2
	v_mov_b32_e32 v22, v2
	v_mov_b32_e32 v23, v2
	v_mov_b32_e32 v24, v2
	v_mov_b32_e32 v25, v2
	v_mov_b32_e32 v34, v2
	v_mov_b32_e32 v35, v2
	v_mov_b32_e32 v36, v2
	v_mov_b32_e32 v37, v2
	v_mov_b32_e32 v38, v2
	v_mov_b32_e32 v39, v2
	v_mov_b32_e32 v40, v2
	v_mov_b32_e32 v41, v2
	v_mov_b32_e32 v50, v2
	v_mov_b32_e32 v51, v2
	v_mov_b32_e32 v52, v2
	v_mov_b32_e32 v53, v2
	v_mov_b32_e32 v54, v2
	v_mov_b32_e32 v55, v2
	v_mov_b32_e32 v56, v2
	v_mov_b32_e32 v57, v2
	v_mov_b32_e32 v10, v2
	v_mov_b32_e32 v11, v2
	v_mov_b32_e32 v12, v2
	v_mov_b32_e32 v13, v2
	v_mov_b32_e32 v14, v2
	v_mov_b32_e32 v15, v2
	v_mov_b32_e32 v16, v2
	v_mov_b32_e32 v17, v2
	v_mov_b32_e32 v26, v2
	v_mov_b32_e32 v27, v2
	v_mov_b32_e32 v28, v2
	v_mov_b32_e32 v29, v2
	v_mov_b32_e32 v30, v2
	v_mov_b32_e32 v31, v2
	v_mov_b32_e32 v32, v2
	v_mov_b32_e32 v33, v2
	v_mov_b32_e32 v42, v2
	v_mov_b32_e32 v43, v2
	v_mov_b32_e32 v44, v2
	v_mov_b32_e32 v45, v2
	v_mov_b32_e32 v46, v2
	v_mov_b32_e32 v47, v2
	v_mov_b32_e32 v48, v2
	v_mov_b32_e32 v49, v2
	v_mov_b32_e32 v58, v2
	v_mov_b32_e32 v59, v2
	v_mov_b32_e32 v60, v2
	v_mov_b32_e32 v61, v2
	v_mov_b32_e32 v62, v2
	v_mov_b32_e32 v63, v2
	v_mov_b32_e32 v64, v2
	v_mov_b32_e32 v65, v2
	v_mov_b32_e32 v66, v2
	v_mov_b32_e32 v67, v2
	v_mov_b32_e32 v68, v2
	v_mov_b32_e32 v69, v2
	v_mov_b32_e32 v70, v2
	v_mov_b32_e32 v71, v2
	v_mov_b32_e32 v72, v2
	v_mov_b32_e32 v73, v2
	v_mov_b32_e32 v82, v2
	v_mov_b32_e32 v83, v2
	v_mov_b32_e32 v84, v2
	v_mov_b32_e32 v85, v2
	v_mov_b32_e32 v86, v2
	v_mov_b32_e32 v87, v2
	v_mov_b32_e32 v88, v2
	v_mov_b32_e32 v89, v2
	v_mov_b32_e32 v98, v2
	v_mov_b32_e32 v99, v2
	v_mov_b32_e32 v100, v2
	v_mov_b32_e32 v101, v2
	v_mov_b32_e32 v102, v2
	v_mov_b32_e32 v103, v2
	v_mov_b32_e32 v104, v2
	v_mov_b32_e32 v105, v2
	v_mov_b32_e32 v130, v2
	v_mov_b32_e32 v131, v2
	v_mov_b32_e32 v132, v2
	v_mov_b32_e32 v133, v2
	v_mov_b32_e32 v134, v2
	v_mov_b32_e32 v135, v2
	v_mov_b32_e32 v136, v2
	v_mov_b32_e32 v137, v2
	v_mov_b32_e32 v74, v2
	v_mov_b32_e32 v75, v2
	v_mov_b32_e32 v76, v2
	v_mov_b32_e32 v77, v2
	v_mov_b32_e32 v78, v2
	v_mov_b32_e32 v79, v2
	v_mov_b32_e32 v80, v2
	v_mov_b32_e32 v81, v2
	v_mov_b32_e32 v90, v2
	v_mov_b32_e32 v91, v2
	v_mov_b32_e32 v92, v2
	v_mov_b32_e32 v93, v2
	v_mov_b32_e32 v94, v2
	v_mov_b32_e32 v95, v2
	v_mov_b32_e32 v96, v2
	v_mov_b32_e32 v97, v2
	v_mov_b32_e32 v106, v2
	v_mov_b32_e32 v107, v2
	v_mov_b32_e32 v108, v2
	v_mov_b32_e32 v109, v2
	v_mov_b32_e32 v110, v2
	v_mov_b32_e32 v111, v2
	v_mov_b32_e32 v112, v2
	v_mov_b32_e32 v113, v2
	v_mov_b32_e32 v138, v2
	v_mov_b32_e32 v139, v2
	v_mov_b32_e32 v140, v2
	v_mov_b32_e32 v141, v2
	v_mov_b32_e32 v142, v2
	v_mov_b32_e32 v143, v2
	v_mov_b32_e32 v144, v2
	v_mov_b32_e32 v145, v2
	s_barrier

.LBB0_1054:
	v_lshrrev_b32_e32 v18, 1, v16
	v_and_b32_e32 v18, 24, v18
	s_add_u32 s10, s6, 0x22012000
	v_and_b32_e32 v17, 15, v16
	v_lshlrev_b32_e32 v19, 1, v18
	v_lshlrev_b32_e32 v16, 2, v16
	s_sext_i32_i16 s25, s4
	s_addc_u32 s11, s7, 0
	v_lshl_or_b32 v137, s15, 6, v17
	v_lshl_or_b32 v17, v17, 6, v19
	s_lshl_b32 s4, s15, 13
	v_and_b32_e32 v16, 32, v16
	v_bitop3_b32 v19, v17, s4, v16 bitop3:0xde
	s_lshl_b32 s4, s14, 5
	s_and_b32 s4, s4, 0x60
	s_add_i32 m0, s82, 0x18000
	v_lshl_add_u64 v[8:9], v[8:9], 0, s[54:55]
	s_lshl_b32 s14, s4, 7
	s_waitcnt vmcnt(2)
	s_barrier
	global_load_lds_dwordx4 v[8:9], off
	v_lshl_add_u64 v[6:7], v[6:7], 0, s[54:55]
	s_add_i32 m0, s82, 0x1a000
	s_add_i32 s71, s82, 0x8000
	s_add_i32 s72, s82, 0xa000
	v_bitop3_b32 v138, v17, s14, v16 bitop3:0xde
	global_load_lds_dwordx4 v[6:7], off
	v_lshl_add_u64 v[2:3], v[2:3], 0, s[54:55]
	s_mov_b32 m0, s71
	s_add_u32 s14, s26, 0x80080
	global_load_lds_dwordx4 v[2:3], off
	v_lshl_add_u64 v[2:3], v[4:5], 0, s[54:55]
	s_mov_b32 m0, s72
	s_addc_u32 s15, s27, 0
	global_load_lds_dwordx4 v[2:3], off
	s_add_i32 m0, s82, 0x1c000
	v_lshl_add_u64 v[2:3], s[14:15], 0, v[0:1]
	global_load_lds_dwordx4 v[2:3], off
	v_lshl_add_u64 v[2:3], s[14:15], 0, v[130:131]
	s_add_i32 m0, s82, 0x1e000
	s_cmpk_lt_u32 s5, 0x100
	global_load_lds_dwordx4 v[2:3], off
	v_lshlrev_b32_e32 v2, 15, v10
	v_and_b32_e32 v2, 0xffff0000, v2
	v_lshl_add_u32 v2, v11, 12, v2
	v_and_b32_e32 v3, 1, v10
	v_lshl_or_b32 v2, v3, 6, v2
	v_lshl_add_u32 v132, v12, 1, v2
	v_lshlrev_b32_e32 v2, 15, v13
	v_and_b32_e32 v2, 0xffff0000, v2
	s_waitcnt vmcnt(6)
	v_lshl_add_u32 v2, v14, 12, v2
	v_and_b32_e32 v3, 1, v13
	v_lshl_or_b32 v2, v3, 6, v2
	s_cselect_b64 s[14:15], -1, 0
	v_or_b32_e32 v139, s4, v18
	v_mov_b32_e32 v133, v1
	v_lshl_add_u32 v134, v15, 1, v2
	v_mov_b32_e32 v135, v1
	s_mov_b32 s65, 0
	v_add_u32_e32 v140, 0, v19
	s_barrier
	s_branch .LBB0_1057

.LBB0_1188:
	v_and_b32_e32 v212, 15, v213
	v_and_b32_e32 v18, 48, v213
	v_lshlrev_b32_e32 v19, 2, v213
	s_and_b32 s33, s17, 3
	s_lshl_b32 s34, s4, 6
	s_lshl_b32 s4, s4, 13
	v_lshl_or_b32 v18, v212, 6, v18
	v_and_b32_e32 v19, 32, v19
	s_add_i32 m0, s61, 0x18000
	v_lshl_add_u64 v[8:9], v[8:9], 0, s[54:55]
	s_lshr_b32 s5, s5, 2
	v_bitop3_b32 v20, v18, s4, v19 bitop3:0xde
	s_lshl_b32 s4, s33, 12
	s_waitcnt vmcnt(2)
	s_barrier
	global_load_lds_dwordx4 v[8:9], off
	v_lshl_add_u64 v[6:7], v[6:7], 0, s[54:55]
	s_add_i32 m0, s61, 0x1a000
	s_add_i32 s68, s61, 0x8000
	s_add_i32 s69, s61, 0xa000
	v_bitop3_b32 v140, v18, s4, v19 bitop3:0xde
	global_load_lds_dwordx4 v[6:7], off
	v_lshl_add_u64 v[4:5], v[4:5], 0, s[54:55]
	s_mov_b32 m0, s68
	s_add_u32 s4, s22, 0x160080
	s_sext_i32_i8 s16, s5
	global_load_lds_dwordx4 v[4:5], off
	v_lshl_add_u64 v[2:3], v[2:3], 0, s[54:55]
	s_mov_b32 m0, s69
	s_addc_u32 s5, s23, 0
	global_load_lds_dwordx4 v[2:3], off
	s_add_i32 m0, s61, 0x1c000
	v_lshl_add_u64 v[2:3], s[4:5], 0, v[0:1]
	global_load_lds_dwordx4 v[2:3], off
	v_lshl_add_u64 v[2:3], s[4:5], 0, v[130:131]
	s_add_i32 m0, s61, 0x1e000
	s_movk_i32 s7, 0x1600
	global_load_lds_dwordx4 v[2:3], off
	v_lshrrev_b32_e32 v3, 1, v14
	v_mul_lo_u32 v2, v16, s7
	s_mov_b32 s6, 0x16000
	v_mad_u64_u32 v[2:3], s[4:5], v3, s6, v[2:3]
	v_or_b32_e32 v2, v2, v15
	v_add_lshl_u32 v132, v2, v17, 1
	v_lshrrev_b32_e32 v3, 1, v10
	v_mul_lo_u32 v2, v12, s7
	v_mad_u64_u32 v[2:3], s[4:5], v3, s6, v[2:3]
	s_waitcnt vmcnt(6)
	v_or_b32_e32 v2, v2, v11
	v_add_lshl_u32 v134, v2, v13, 1
	v_mov_b32_e32 v2, 0
	v_or_b32_e32 v211, s34, v212
	v_mov_b32_e32 v133, v1
	v_mov_b32_e32 v135, v1
	s_mov_b32 s70, 0
	v_add_u32_e32 v141, 0, v20
	v_mov_b32_e32 v3, v2
	v_mov_b32_e32 v4, v2
	v_mov_b32_e32 v5, v2
	v_mov_b32_e32 v6, v2
	v_mov_b32_e32 v7, v2
	v_mov_b32_e32 v8, v2
	v_mov_b32_e32 v9, v2
	v_mov_b32_e32 v14, v2
	v_mov_b32_e32 v15, v2
	v_mov_b32_e32 v16, v2
	v_mov_b32_e32 v17, v2
	v_mov_b32_e32 v22, v2
	v_mov_b32_e32 v23, v2
	v_mov_b32_e32 v24, v2
	v_mov_b32_e32 v25, v2
	v_mov_b32_e32 v30, v2
	v_mov_b32_e32 v31, v2
	v_mov_b32_e32 v32, v2
	v_mov_b32_e32 v33, v2
	v_mov_b32_e32 v38, v2
	v_mov_b32_e32 v39, v2
	v_mov_b32_e32 v40, v2
	v_mov_b32_e32 v41, v2
	v_mov_b32_e32 v46, v2
	v_mov_b32_e32 v47, v2
	v_mov_b32_e32 v48, v2
	v_mov_b32_e32 v49, v2
	v_mov_b32_e32 v54, v2
	v_mov_b32_e32 v55, v2
	v_mov_b32_e32 v56, v2
	v_mov_b32_e32 v57, v2
	v_mov_b32_e32 v10, v2
	v_mov_b32_e32 v11, v2
	v_mov_b32_e32 v12, v2
	v_mov_b32_e32 v13, v2
	v_mov_b32_e32 v18, v2
	v_mov_b32_e32 v19, v2
	v_mov_b32_e32 v20, v2
	v_mov_b32_e32 v21, v2
	v_mov_b32_e32 v26, v2
	v_mov_b32_e32 v27, v2
	v_mov_b32_e32 v28, v2
	v_mov_b32_e32 v29, v2
	v_mov_b32_e32 v34, v2
	v_mov_b32_e32 v35, v2
	v_mov_b32_e32 v36, v2
	v_mov_b32_e32 v37, v2
	v_mov_b32_e32 v42, v2
	v_mov_b32_e32 v43, v2
	v_mov_b32_e32 v44, v2
	v_mov_b32_e32 v45, v2
	v_mov_b32_e32 v50, v2
	v_mov_b32_e32 v51, v2
	v_mov_b32_e32 v52, v2
	v_mov_b32_e32 v53, v2
	v_mov_b32_e32 v58, v2
	v_mov_b32_e32 v59, v2
	v_mov_b32_e32 v60, v2
	v_mov_b32_e32 v61, v2
	v_mov_b32_e32 v62, v2
	v_mov_b32_e32 v63, v2
	v_mov_b32_e32 v64, v2
	v_mov_b32_e32 v65, v2
	v_mov_b32_e32 v66, v2
	v_mov_b32_e32 v67, v2
	v_mov_b32_e32 v68, v2
	v_mov_b32_e32 v69, v2
	v_mov_b32_e32 v70, v2
	v_mov_b32_e32 v71, v2
	v_mov_b32_e32 v72, v2
	v_mov_b32_e32 v73, v2
	v_mov_b32_e32 v78, v2
	v_mov_b32_e32 v79, v2
	v_mov_b32_e32 v80, v2
	v_mov_b32_e32 v81, v2
	v_mov_b32_e32 v86, v2
	v_mov_b32_e32 v87, v2
	v_mov_b32_e32 v88, v2
	v_mov_b32_e32 v89, v2
	v_mov_b32_e32 v94, v2
	v_mov_b32_e32 v95, v2
	v_mov_b32_e32 v96, v2
	v_mov_b32_e32 v97, v2
	v_mov_b32_e32 v102, v2
	v_mov_b32_e32 v103, v2
	v_mov_b32_e32 v104, v2
	v_mov_b32_e32 v105, v2
	v_mov_b32_e32 v114, v2
	v_mov_b32_e32 v115, v2
	v_mov_b32_e32 v116, v2
	v_mov_b32_e32 v117, v2
	v_mov_b32_e32 v118, v2
	v_mov_b32_e32 v119, v2
	v_mov_b32_e32 v120, v2
	v_mov_b32_e32 v121, v2
	v_mov_b32_e32 v74, v2
	v_mov_b32_e32 v75, v2
	v_mov_b32_e32 v76, v2
	v_mov_b32_e32 v77, v2
	v_mov_b32_e32 v82, v2
	v_mov_b32_e32 v83, v2
	v_mov_b32_e32 v84, v2
	v_mov_b32_e32 v85, v2
	v_mov_b32_e32 v90, v2
	v_mov_b32_e32 v91, v2
	v_mov_b32_e32 v92, v2
	v_mov_b32_e32 v93, v2
	v_mov_b32_e32 v98, v2
	v_mov_b32_e32 v99, v2
	v_mov_b32_e32 v100, v2
	v_mov_b32_e32 v101, v2
	v_mov_b32_e32 v106, v2
	v_mov_b32_e32 v107, v2
	v_mov_b32_e32 v108, v2
	v_mov_b32_e32 v109, v2
	v_mov_b32_e32 v110, v2
	v_mov_b32_e32 v111, v2
	v_mov_b32_e32 v112, v2
	v_mov_b32_e32 v113, v2
	v_mov_b32_e32 v122, v2
	v_mov_b32_e32 v123, v2
	v_mov_b32_e32 v124, v2
	v_mov_b32_e32 v125, v2
	v_mov_b32_e32 v126, v2
	v_mov_b32_e32 v127, v2
	v_mov_b32_e32 v128, v2
	v_mov_b32_e32 v129, v2
	s_barrier
